# prep x->bf16 stream: non-temporal (nt) hint on the once-read f32 input loads
# speedup vs baseline: 1.0106x; 1.0023x over previous
.LBB0_301:
	s_andn2_saveexec_b64 s[2:3], s[2:3]
	s_cbranch_execz .LBB0_310
	v_mad_u64_u32 v[0:1], s[4:5], s90, 6, v[0:1]
	s_movk_i32 s4, 0x4200
	s_nop 0
	v_cmp_gt_i32_e32 vcc, s4, v0
	s_and_saveexec_b64 s[4:5], vcc
	s_movk_i32 s14, 0x3fff
	s_cbranch_execz .LBB0_309
	v_and_b32_e32 v1, 64, v190
	s_waitcnt vmcnt(1)
	v_lshlrev_b32_e32 v8, 2, v4
	v_lshlrev_b32_e32 v2, 3, v4
	v_cmp_gt_u32_e32 vcc, 16, v4
	v_cmp_eq_u32_e64 s[38:39], 0, v4
	v_add_u32_e32 v1, 64, v1
	v_xor_b32_e32 v4, 1, v190
	v_cmp_lt_i32_e64 s[40:41], v4, v1
	s_load_dwordx4 s[44:47], s[0:1], 0x0
	s_mul_i32 s0, s74, 6
	v_cndmask_b32_e64 v4, v190, v4, s[40:41]
	s_waitcnt vmcnt(0)
	v_lshlrev_b32_e32 v14, 2, v4
	v_xor_b32_e32 v4, 2, v190
	v_cmp_lt_i32_e64 s[40:41], v4, v1
	v_mov_b32_e32 v9, v20
	v_mov_b32_e32 v3, v20
	v_cndmask_b32_e64 v4, v190, v4, s[40:41]
	v_lshlrev_b32_e32 v15, 2, v4
	v_xor_b32_e32 v4, 4, v190
	v_cmp_lt_i32_e64 s[40:41], v4, v1
	s_ashr_i32 s1, s0, 31
	v_lshl_add_u64 v[2:3], s[18:19], 0, v[2:3]
	v_cndmask_b32_e64 v4, v190, v4, s[40:41]
	v_lshlrev_b32_e32 v16, 2, v4
	v_xor_b32_e32 v4, 8, v190
	v_cmp_lt_i32_e64 s[40:41], v4, v1
	v_lshl_add_u64 v[6:7], s[78:79], 0, v[8:9]
	s_lshl_b64 s[6:7], s[0:1], 12
	v_cndmask_b32_e64 v4, v190, v4, s[40:41]
	v_lshlrev_b32_e32 v17, 2, v4
	v_xor_b32_e32 v4, 16, v190
	v_cmp_lt_i32_e64 s[40:41], v4, v1
	s_mov_b64 s[8:9], 0
	v_lshlrev_b32_e32 v8, 2, v8
	v_cndmask_b32_e64 v4, v190, v4, s[40:41]
	v_lshlrev_b32_e32 v18, 2, v4
	v_xor_b32_e32 v4, 32, v190
	v_cmp_lt_i32_e64 s[40:41], v4, v1
	s_nop 1
	v_cndmask_b32_e64 v1, v190, v4, s[40:41]
	v_lshlrev_b32_e32 v19, 2, v1
	v_ashrrev_i32_e32 v1, 31, v0
	v_lshlrev_b64 v[4:5], 12, v[0:1]
	s_waitcnt lgkmcnt(0)
	v_lshl_add_u64 v[4:5], s[44:45], 0, v[4:5]
	v_lshrrev_b32_e32 v48, 1, v8
	v_readfirstlane_b32 s8, v0
	s_nop 3
	s_cmp_gt_i32 s8, 0x3fff
	s_cselect_b32 s10, s46, s44
	s_cselect_b32 s11, s47, s45
	s_cselect_b32 s1, 0x4000, 0
	s_sub_i32 s1, s8, s1
	s_lshl_b32 s1, s1, 12
	s_add_u32 s10, s10, s1
	s_addc_u32 s11, s11, 0
	global_load_dwordx4 v[22:25], v8, s[10:11] nt
	global_load_dwordx4 v[26:29], v8, s[10:11] offset:1024 nt
	global_load_dwordx4 v[30:33], v8, s[10:11] offset:2048 nt
	global_load_dwordx4 v[34:37], v8, s[10:11] offset:3072 nt
	s_add_i32 s9, s8, s0
	s_cmp_le_i32 s9, 0x41ff
	s_cselect_b32 s14, s9, s8
	s_cmp_gt_i32 s14, 0x3fff
	s_cselect_b32 s6, s46, s44
	s_cselect_b32 s7, s47, s45
	s_cselect_b32 s1, 0x4000, 0
	s_sub_i32 s1, s14, s1
	s_lshl_b32 s1, s1, 12
	s_add_u32 s6, s6, s1
	s_addc_u32 s7, s7, 0
	global_load_dwordx4 v[74:77], v8, s[6:7] nt
	global_load_dwordx4 v[78:81], v8, s[6:7] offset:1024 nt
	global_load_dwordx4 v[82:85], v8, s[6:7] offset:2048 nt
	global_load_dwordx4 v[86:89], v8, s[6:7] offset:3072 nt
	s_lshl_b32 s1, s8, 11
	s_add_u32 s40, s18, s1
	s_addc_u32 s41, s19, 0
	s_waitcnt vmcnt(7)
	v_cvt_pk_bf16_f32 v40, v22, v23
	v_cvt_pk_bf16_f32 v41, v24, v25
	global_store_dwordx2 v48, v[40:41], s[40:41]
	v_mul_f32_e32 v9, v23, v23
	v_fmac_f32_e32 v9, v22, v22
	v_fmac_f32_e32 v9, v24, v24
	v_fmac_f32_e32 v9, v25, v25
	s_waitcnt vmcnt(7)
	v_cvt_pk_bf16_f32 v42, v26, v27
	v_cvt_pk_bf16_f32 v43, v28, v29
	global_store_dwordx2 v48, v[42:43], s[40:41] offset:512
	v_mul_f32_e32 v12, v27, v27
	v_fmac_f32_e32 v12, v26, v26
	v_fmac_f32_e32 v12, v28, v28
	v_fmac_f32_e32 v12, v29, v29
	v_add_f32_e32 v9, v9, v12
	s_waitcnt vmcnt(7)
	v_cvt_pk_bf16_f32 v44, v30, v31
	v_cvt_pk_bf16_f32 v45, v32, v33
	global_store_dwordx2 v48, v[44:45], s[40:41] offset:1024
	v_mul_f32_e32 v12, v31, v31
	v_fmac_f32_e32 v12, v30, v30
	v_fmac_f32_e32 v12, v32, v32
	v_fmac_f32_e32 v12, v33, v33
	v_add_f32_e32 v9, v9, v12
	s_waitcnt vmcnt(7)
	v_cvt_pk_bf16_f32 v46, v34, v35
	v_cvt_pk_bf16_f32 v47, v36, v37
	global_store_dwordx2 v48, v[46:47], s[40:41] offset:1536
	v_mul_f32_e32 v12, v35, v35
	v_fmac_f32_e32 v12, v34, v34
	v_fmac_f32_e32 v12, v36, v36
	v_fmac_f32_e32 v12, v37, v37
	v_add_f32_e32 v9, v9, v12
	ds_bpermute_b32 v12, v14, v9
	s_waitcnt lgkmcnt(0)
	v_add_f32_e32 v9, v9, v12
	ds_bpermute_b32 v12, v15, v9
	s_waitcnt lgkmcnt(0)
	v_add_f32_e32 v9, v9, v12
	ds_bpermute_b32 v12, v16, v9
	s_waitcnt lgkmcnt(0)
	v_add_f32_e32 v9, v9, v12
	ds_bpermute_b32 v12, v17, v9
	s_waitcnt lgkmcnt(0)
	v_add_f32_e32 v9, v9, v12
	ds_bpermute_b32 v12, v18, v9
	s_waitcnt lgkmcnt(0)
	v_add_f32_e32 v9, v9, v12
	ds_bpermute_b32 v12, v19, v9
	v_mov_b32_e32 v10, s8
	v_mov_b32_e32 v11, v20
	v_lshlrev_b64 v[10:11], 6, v[10:11]
	v_lshl_add_u64 v[10:11], v[6:7], 0, v[10:11]
	s_waitcnt lgkmcnt(0)
	v_add_f32_e32 v9, v9, v12
	v_cndmask_b32_e64 v9, 0, v9, s[38:39]
	s_mov_b64 exec, vcc
	global_store_dword v[10:11], v9, off
	s_mov_b64 exec, -1
	s_cmp_gt_i32 s9, 0x41ff
	s_cbranch_scc1 .Lt2_exit
	s_mov_b32 s8, s9
.Lt2_loop:
	s_add_i32 s9, s8, s0
	s_cmp_le_i32 s9, 0x41ff
	s_cselect_b32 s14, s9, s8
	s_cmp_gt_i32 s14, 0x3fff
	s_cselect_b32 s10, s46, s44
	s_cselect_b32 s11, s47, s45
	s_cselect_b32 s1, 0x4000, 0
	s_sub_i32 s1, s14, s1
	s_lshl_b32 s1, s1, 12
	s_add_u32 s10, s10, s1
	s_addc_u32 s11, s11, 0
	global_load_dwordx4 v[22:25], v8, s[10:11] nt
	global_load_dwordx4 v[26:29], v8, s[10:11] offset:1024 nt
	global_load_dwordx4 v[30:33], v8, s[10:11] offset:2048 nt
	global_load_dwordx4 v[34:37], v8, s[10:11] offset:3072 nt
	s_lshl_b32 s1, s8, 11
	s_add_u32 s40, s18, s1
	s_addc_u32 s41, s19, 0
	s_waitcnt vmcnt(12)
	v_cvt_pk_bf16_f32 v40, v74, v75
	v_cvt_pk_bf16_f32 v41, v76, v77
	global_store_dwordx2 v48, v[40:41], s[40:41]
	v_mul_f32_e32 v9, v75, v75
	v_fmac_f32_e32 v9, v74, v74
	v_fmac_f32_e32 v9, v76, v76
	v_fmac_f32_e32 v9, v77, v77
	s_waitcnt vmcnt(12)
	v_cvt_pk_bf16_f32 v42, v78, v79
	v_cvt_pk_bf16_f32 v43, v80, v81
	global_store_dwordx2 v48, v[42:43], s[40:41] offset:512
	v_mul_f32_e32 v12, v79, v79
	v_fmac_f32_e32 v12, v78, v78
	v_fmac_f32_e32 v12, v80, v80
	v_fmac_f32_e32 v12, v81, v81
	v_add_f32_e32 v9, v9, v12
	s_waitcnt vmcnt(12)
	v_cvt_pk_bf16_f32 v44, v82, v83
	v_cvt_pk_bf16_f32 v45, v84, v85
	global_store_dwordx2 v48, v[44:45], s[40:41] offset:1024
	v_mul_f32_e32 v12, v83, v83
	v_fmac_f32_e32 v12, v82, v82
	v_fmac_f32_e32 v12, v84, v84
	v_fmac_f32_e32 v12, v85, v85
	v_add_f32_e32 v9, v9, v12
	s_waitcnt vmcnt(12)
	v_cvt_pk_bf16_f32 v46, v86, v87
	v_cvt_pk_bf16_f32 v47, v88, v89
	global_store_dwordx2 v48, v[46:47], s[40:41] offset:1536
	v_mul_f32_e32 v12, v87, v87
	v_fmac_f32_e32 v12, v86, v86
	v_fmac_f32_e32 v12, v88, v88
	v_fmac_f32_e32 v12, v89, v89
	v_add_f32_e32 v9, v9, v12
	ds_bpermute_b32 v12, v14, v9
	s_waitcnt lgkmcnt(0)
	v_add_f32_e32 v9, v9, v12
	ds_bpermute_b32 v12, v15, v9
	s_waitcnt lgkmcnt(0)
	v_add_f32_e32 v9, v9, v12
	ds_bpermute_b32 v12, v16, v9
	s_waitcnt lgkmcnt(0)
	v_add_f32_e32 v9, v9, v12
	ds_bpermute_b32 v12, v17, v9
	s_waitcnt lgkmcnt(0)
	v_add_f32_e32 v9, v9, v12
	ds_bpermute_b32 v12, v18, v9
	s_waitcnt lgkmcnt(0)
	v_add_f32_e32 v9, v9, v12
	ds_bpermute_b32 v12, v19, v9
	v_mov_b32_e32 v10, s8
	v_mov_b32_e32 v11, v20
	v_lshlrev_b64 v[10:11], 6, v[10:11]
	v_lshl_add_u64 v[10:11], v[6:7], 0, v[10:11]
	s_waitcnt lgkmcnt(0)
	v_add_f32_e32 v9, v9, v12
	v_cndmask_b32_e64 v9, 0, v9, s[38:39]
	s_mov_b64 exec, vcc
	global_store_dword v[10:11], v9, off
	s_mov_b64 exec, -1
	s_cmp_gt_i32 s9, 0x41ff
	s_cbranch_scc1 .Lt2_exit
	s_mov_b32 s8, s9
	s_add_i32 s9, s8, s0
	s_cmp_le_i32 s9, 0x41ff
	s_cselect_b32 s14, s9, s8
	s_cmp_gt_i32 s14, 0x3fff
	s_cselect_b32 s6, s46, s44
	s_cselect_b32 s7, s47, s45
	s_cselect_b32 s1, 0x4000, 0
	s_sub_i32 s1, s14, s1
	s_lshl_b32 s1, s1, 12
	s_add_u32 s6, s6, s1
	s_addc_u32 s7, s7, 0
	global_load_dwordx4 v[74:77], v8, s[6:7] nt
	global_load_dwordx4 v[78:81], v8, s[6:7] offset:1024 nt
	global_load_dwordx4 v[82:85], v8, s[6:7] offset:2048 nt
	global_load_dwordx4 v[86:89], v8, s[6:7] offset:3072 nt
	s_lshl_b32 s1, s8, 11
	s_add_u32 s40, s18, s1
	s_addc_u32 s41, s19, 0
	s_waitcnt vmcnt(12)
	v_cvt_pk_bf16_f32 v40, v22, v23
	v_cvt_pk_bf16_f32 v41, v24, v25
	global_store_dwordx2 v48, v[40:41], s[40:41]
	v_mul_f32_e32 v9, v23, v23
	v_fmac_f32_e32 v9, v22, v22
	v_fmac_f32_e32 v9, v24, v24
	v_fmac_f32_e32 v9, v25, v25
	s_waitcnt vmcnt(12)
	v_cvt_pk_bf16_f32 v42, v26, v27
	v_cvt_pk_bf16_f32 v43, v28, v29
	global_store_dwordx2 v48, v[42:43], s[40:41] offset:512
	v_mul_f32_e32 v12, v27, v27
	v_fmac_f32_e32 v12, v26, v26
	v_fmac_f32_e32 v12, v28, v28
	v_fmac_f32_e32 v12, v29, v29
	v_add_f32_e32 v9, v9, v12
	s_waitcnt vmcnt(12)
	v_cvt_pk_bf16_f32 v44, v30, v31
	v_cvt_pk_bf16_f32 v45, v32, v33
	global_store_dwordx2 v48, v[44:45], s[40:41] offset:1024
	v_mul_f32_e32 v12, v31, v31
	v_fmac_f32_e32 v12, v30, v30
	v_fmac_f32_e32 v12, v32, v32
	v_fmac_f32_e32 v12, v33, v33
	v_add_f32_e32 v9, v9, v12
	s_waitcnt vmcnt(12)
	v_cvt_pk_bf16_f32 v46, v34, v35
	v_cvt_pk_bf16_f32 v47, v36, v37
	global_store_dwordx2 v48, v[46:47], s[40:41] offset:1536
	v_mul_f32_e32 v12, v35, v35
	v_fmac_f32_e32 v12, v34, v34
	v_fmac_f32_e32 v12, v36, v36
	v_fmac_f32_e32 v12, v37, v37
	v_add_f32_e32 v9, v9, v12
	ds_bpermute_b32 v12, v14, v9
	s_waitcnt lgkmcnt(0)
	v_add_f32_e32 v9, v9, v12
	ds_bpermute_b32 v12, v15, v9
	s_waitcnt lgkmcnt(0)
	v_add_f32_e32 v9, v9, v12
	ds_bpermute_b32 v12, v16, v9
	s_waitcnt lgkmcnt(0)
	v_add_f32_e32 v9, v9, v12
	ds_bpermute_b32 v12, v17, v9
	s_waitcnt lgkmcnt(0)
	v_add_f32_e32 v9, v9, v12
	ds_bpermute_b32 v12, v18, v9
	s_waitcnt lgkmcnt(0)
	v_add_f32_e32 v9, v9, v12
	ds_bpermute_b32 v12, v19, v9
	v_mov_b32_e32 v10, s8
	v_mov_b32_e32 v11, v20
	v_lshlrev_b64 v[10:11], 6, v[10:11]
	v_lshl_add_u64 v[10:11], v[6:7], 0, v[10:11]
	s_waitcnt lgkmcnt(0)
	v_add_f32_e32 v9, v9, v12
	v_cndmask_b32_e64 v9, 0, v9, s[38:39]
	s_mov_b64 exec, vcc
	global_store_dword v[10:11], v9, off
	s_mov_b64 exec, -1
	s_cmp_gt_i32 s9, 0x41ff
	s_cbranch_scc1 .Lt2_exit
	s_mov_b32 s8, s9
	s_branch .Lt2_loop
